# v6 with stage-1 sample items dealt by permuted workgroup index (9-chunk chain segments take 6 items, 8-chunk segments 7), NEARLY back to 384
# speedup vs baseline: 1.0056x; 1.0056x over previous
.LBB0_302:
	v_writelane_b32 v253, s88, 24
	s_nop 1
	v_writelane_b32 v253, s89, 25
	v_writelane_b32 v253, s60, 26
	s_nop 1
	v_writelane_b32 v253, s61, 27
	v_writelane_b32 v253, s68, 28
	s_nop 1
	v_writelane_b32 v253, s69, 29
	s_or_b64 exec, exec, s[0:1]
	s_ashr_i32 s0, s90, 31
	s_add_u32 s30, s70, 0xd600000
	s_addc_u32 s31, s71, 0
	s_add_u32 s8, s70, 0x6700000
	s_addc_u32 s9, s71, 0
	s_add_u32 s6, s70, 0x8c00000
	s_addc_u32 s7, s71, 0
	s_add_u32 s14, s70, 0xb100000
	s_addc_u32 s15, s71, 0
	s_cmpk_lg_i32 s90, 0x100
	v_writelane_b32 v253, s0, 30
	s_cselect_b64 s[0:1], -1, 0
	v_writelane_b32 v253, s0, 31
	v_lshl_add_u64 v[2:3], v[2:3], 2, s[36:37]
	s_mov_b64 s[48:49], s[84:85]
	v_writelane_b32 v253, s1, 32
	s_mov_b64 s[50:51], s[86:87]
	v_readlane_b32 s10, v253, 0
	s_and_b32 s0, s10, 3
	s_cmp_eq_u32 s0, 3
	s_cselect_b64 s[0:1], -1, 0
	s_cmpk_eq_i32 s90, 0x100
	s_cselect_b64 s[12:13], -1, 0
	s_and_b64 s[2:3], s[12:13], exec
	s_cselect_b32 s4, 0x180, 0
	s_and_b64 s[0:1], s[0:1], s[12:13]
	s_ashr_i32 s5, s10, 2
	s_bitcmp1_b32 s10, 2
	s_cselect_b64 s[2:3], -1, 0
	v_writelane_b32 v253, s12, 33
	s_and_b64 s[2:3], s[2:3], s[12:13]
	s_and_b64 s[0:1], s[0:1], exec
	v_writelane_b32 v253, s13, 34
	s_cselect_b32 s0, s5, 0x1000
	v_writelane_b32 v253, s0, 35
	s_and_b32 s98, s10, 3
	s_lshr_b32 s99, s98, 1
	s_xor_b32 s100, s98, s99
	s_and_b32 s100, s100, 1
	s_xor_b32 s100, s100, 1
	s_lshl_b32 s100, s100, 7
	s_lshr_b32 s101, s10, 2
	s_lshl_b32 s101, s101, 1
	s_or_b32 s101, s101, s99
	s_or_b32 s101, s101, s100
	s_add_i32 s0, s4, s101
	s_cmpk_lt_i32 s10, 0x100
	v_writelane_b32 v253, s0, 36
	s_cselect_b64 s[0:1], -1, 0
	v_writelane_b32 v253, s0, 37
	s_cmpk_gt_i32 s10, 0xff
	s_mov_b64 s[36:37], s[72:73]
	v_writelane_b32 v253, s1, 38
	s_cselect_b64 s[0:1], -1, 0
	v_writelane_b32 v253, s0, 39
	s_mov_b64 s[42:43], s[78:79]
	s_mov_b64 s[46:47], s[82:83]
	v_writelane_b32 v253, s1, 40
	v_writelane_b32 v253, s2, 41
	s_xor_b64 s[0:1], s[2:3], -1
	s_waitcnt lgkmcnt(0)
	v_writelane_b32 v253, s3, 42
	v_writelane_b32 v253, s0, 43
	s_barrier
	s_nop 0
	v_writelane_b32 v253, s1, 44
	s_add_u32 s0, s70, 0x19846000
	v_writelane_b32 v253, s0, 45
	s_addc_u32 s0, s71, 0
	v_writelane_b32 v253, s0, 46
	s_add_u32 s0, s70, 0x1a846000
	s_addc_u32 s1, s71, 0
	v_writelane_b32 v253, s0, 47
	v_mov_b32_e32 v147, 0
	v_mov_b32_e32 v1, 0x358637bd
	v_writelane_b32 v253, s1, 48
	s_add_u32 s0, s86, 0x4800000
	v_writelane_b32 v253, s0, 49
	s_addc_u32 s0, s87, 0
	s_add_u32 s96, s70, 0x19842200
	s_addc_u32 s97, s71, 0
	v_writelane_b32 v253, s0, 50
	s_add_u32 s0, s70, 0x19842400
	s_addc_u32 s1, s71, 0
	v_writelane_b32 v253, s0, 51
	v_mov_b32_e32 v168, 1
	s_mov_b32 s33, 0x800000
	v_writelane_b32 v253, s1, 52
	s_add_u32 s0, s70, 0x19842500
	s_addc_u32 s1, s71, 0
	v_writelane_b32 v253, s0, 53
	s_movk_i32 s13, 0x110
	s_movk_i32 s18, 0x810
	v_writelane_b32 v253, s1, 54
	s_add_u32 s0, s70, 0x19842600
	s_addc_u32 s1, s71, 0
	v_writelane_b32 v253, s0, 55
	s_movk_i32 s25, 0x7fff
	s_mov_b64 s[16:17], -1
	v_writelane_b32 v253, s1, 56
	s_add_u32 s0, s70, 0x19842700
	s_addc_u32 s1, s71, 0
	v_writelane_b32 v253, s0, 57
	s_mov_b64 s[94:95], 0x10000
	s_nop 0
	v_writelane_b32 v253, s1, 58
	s_add_u32 s0, s70, 0x19842800
	s_addc_u32 s1, s71, 0
	v_writelane_b32 v253, s0, 59
	s_nop 1
	v_writelane_b32 v253, s1, 60
	s_add_u32 s0, s70, 0x19842900
	s_addc_u32 s1, s71, 0
	v_writelane_b32 v253, s0, 61
	s_nop 1
	v_writelane_b32 v253, s1, 62
	s_add_u32 s0, s70, 0x19842a00
	s_addc_u32 s1, s71, 0
	v_writelane_b32 v253, s0, 63
	s_nop 1
	v_writelane_b32 v254, s1, 0
	s_add_u32 s0, s70, 0x19842b00
	s_addc_u32 s1, s71, 0
	v_writelane_b32 v254, s0, 1
	s_nop 1
	v_writelane_b32 v254, s1, 2
	s_add_u32 s0, s70, 0x19842c00
	s_addc_u32 s1, s71, 0
	v_writelane_b32 v254, s0, 3
	s_nop 1
	v_writelane_b32 v254, s1, 4
	s_add_u32 s0, s70, 0x19842d00
	s_addc_u32 s1, s71, 0
	v_writelane_b32 v254, s0, 5
	s_nop 1
	v_writelane_b32 v254, s1, 6
	s_add_u32 s0, s70, 0x19842e00
	s_addc_u32 s1, s71, 0
	v_writelane_b32 v254, s0, 7
	s_nop 1
	v_writelane_b32 v254, s1, 8
	s_add_u32 s0, s70, 0x19842f00
	s_addc_u32 s1, s71, 0
	v_writelane_b32 v254, s0, 9
	s_nop 1
	v_writelane_b32 v254, s1, 10
	s_add_u32 s0, s70, 0x19843000
	s_addc_u32 s1, s71, 0
	v_writelane_b32 v254, s0, 11
	s_nop 1
	v_writelane_b32 v254, s1, 12
	s_add_u32 s0, s70, 0x19843100
	s_addc_u32 s1, s71, 0
	v_writelane_b32 v254, s0, 13
	s_nop 1
	v_writelane_b32 v254, s1, 14
	s_add_u32 s0, s70, 0x19843200
	s_addc_u32 s1, s71, 0
	v_writelane_b32 v254, s0, 15
	s_nop 1
	v_writelane_b32 v254, s1, 16
	s_add_u32 s0, s70, 0x19843300
	s_addc_u32 s1, s71, 0
	v_writelane_b32 v254, s0, 17
	s_cmp_eq_u32 s66, 15
	s_nop 0
	v_writelane_b32 v254, s1, 18
	s_cselect_b64 s[0:1], -1, 0
	v_writelane_b32 v254, s0, 19
	s_cmp_eq_u32 s66, 14
	s_nop 0
	v_writelane_b32 v254, s1, 20
	s_cselect_b64 s[0:1], -1, 0
	v_writelane_b32 v254, s0, 21
	s_cmp_eq_u32 s66, 13
	s_nop 0
	v_writelane_b32 v254, s1, 22
	s_cselect_b64 s[0:1], -1, 0
	v_writelane_b32 v254, s0, 23
	s_cmp_eq_u32 s66, 12
	s_nop 0
	v_writelane_b32 v254, s1, 24
	s_cselect_b64 s[0:1], -1, 0
	v_writelane_b32 v254, s0, 25
	s_cmp_eq_u32 s66, 11
	s_nop 0
	v_writelane_b32 v254, s1, 26
	s_cselect_b64 s[0:1], -1, 0
	v_writelane_b32 v254, s0, 27
	s_cmp_eq_u32 s66, 10
	s_nop 0
	v_writelane_b32 v254, s1, 28
	s_mov_b64 s[0:1], 0x1400
	v_lshl_add_u64 v[156:157], v[2:3], 0, s[0:1]
	s_mov_b64 s[0:1], 0x2400
	v_lshl_add_u64 v[154:155], v[2:3], 0, s[0:1]
	s_cselect_b64 s[0:1], -1, 0
	v_writelane_b32 v254, s0, 29
	s_cmp_eq_u32 s66, 9
	v_mbcnt_lo_u32_b32 v2, -1, 0
	v_writelane_b32 v254, s1, 30
	s_cselect_b64 s[0:1], -1, 0
	v_writelane_b32 v254, s0, 31
	s_cmp_eq_u32 s66, 8
	v_mbcnt_hi_u32_b32 v175, -1, v2
	v_writelane_b32 v254, s1, 32
	s_cselect_b64 s[0:1], -1, 0
	v_writelane_b32 v254, s0, 33
	s_cmp_eq_u32 s66, 7
	s_nop 0
	v_writelane_b32 v254, s1, 34
	s_cselect_b64 s[0:1], -1, 0
	v_writelane_b32 v254, s0, 35
	s_cmp_eq_u32 s66, 6
	s_nop 0
	v_writelane_b32 v254, s1, 36
	s_cselect_b64 s[0:1], -1, 0
	v_writelane_b32 v254, s0, 37
	s_cmp_eq_u32 s66, 5
	s_nop 0
	v_writelane_b32 v254, s1, 38
	s_cselect_b64 s[0:1], -1, 0
	v_writelane_b32 v254, s0, 39
	s_cmp_eq_u32 s66, 4
	s_nop 0
	v_writelane_b32 v254, s1, 40
	s_cselect_b64 s[0:1], -1, 0
	v_writelane_b32 v254, s0, 41
	s_cmp_eq_u32 s66, 3
	s_nop 0
	v_writelane_b32 v254, s1, 42
	s_cselect_b64 s[0:1], -1, 0
	v_writelane_b32 v254, s0, 43
	s_cmp_eq_u32 s66, 2
	s_nop 0
	v_writelane_b32 v254, s1, 44
	s_cselect_b64 s[0:1], -1, 0
	v_writelane_b32 v254, s0, 45
	s_cmp_eq_u32 s66, 1
	s_nop 0
	v_writelane_b32 v254, s1, 46
	s_cselect_b64 s[0:1], -1, 0
	v_writelane_b32 v254, s0, 47
	s_cmp_eq_u32 s66, 0
	s_nop 0
	v_writelane_b32 v254, s1, 48
	s_cselect_b64 s[0:1], -1, 0
	v_writelane_b32 v254, s0, 49
	s_nop 1
	v_writelane_b32 v254, s1, 50
	s_add_u32 s0, s70, 0x19845400
	s_addc_u32 s1, s71, 0
	v_writelane_b32 v254, s0, 51
	s_nop 1
	v_writelane_b32 v254, s1, 52
	s_add_u32 s0, s70, 0x19845500
	s_addc_u32 s1, s71, 0
	v_writelane_b32 v254, s0, 53
	s_nop 1
	v_writelane_b32 v254, s1, 54
	s_add_u32 s0, s86, 0x4c00000
	v_writelane_b32 v254, s0, 55
	s_addc_u32 s0, s87, 0
	v_writelane_b32 v254, s0, 56
	s_add_u32 s0, s70, 0x19846400
	v_writelane_b32 v254, s0, 57
	v_writelane_b32 v254, s70, 58
	s_addc_u32 s0, s71, 0
	s_nop 0
	v_writelane_b32 v254, s71, 59
	v_writelane_b32 v254, s0, 60
	s_add_i32 s0, 0, 0x13c00
	v_writelane_b32 v254, s0, 61
	s_add_i32 s0, 0, 0x1c600
	v_writelane_b32 v254, s0, 62
	s_add_i32 s0, 0, 0x1c400
	v_writelane_b32 v254, s0, 63
	s_add_i32 s0, 0, 0x11800
	v_writelane_b32 v255, s0, 0
	s_add_i32 s0, 0, 0x20000
	v_writelane_b32 v255, s0, 1
	s_add_i32 s0, 0, 0x20004
	v_writelane_b32 v255, s0, 2
	v_writelane_b32 v255, s36, 3
	v_readlane_b32 s56, v253, 5
	v_readlane_b32 s57, v253, 6
	v_writelane_b32 v255, s37, 4
	v_writelane_b32 v255, s38, 5
	v_writelane_b32 v255, s39, 6
	v_writelane_b32 v255, s40, 7
	v_writelane_b32 v255, s41, 8
	v_writelane_b32 v255, s42, 9
	v_writelane_b32 v255, s43, 10
	v_writelane_b32 v255, s44, 11
	v_writelane_b32 v255, s45, 12
	v_writelane_b32 v255, s46, 13
	v_writelane_b32 v255, s47, 14
	v_writelane_b32 v255, s48, 15
	v_writelane_b32 v255, s49, 16
	v_writelane_b32 v255, s50, 17
	v_writelane_b32 v255, s51, 18
	v_writelane_b32 v255, s90, 19
	v_writelane_b32 v255, s96, 20
	v_readlane_b32 s58, v253, 7
	v_readlane_b32 s59, v253, 8
	v_readlane_b32 s60, v253, 9
	v_readlane_b32 s61, v253, 10
	v_readlane_b32 s62, v253, 11
	v_readlane_b32 s63, v253, 12
	v_readlane_b32 s64, v253, 13
	v_readlane_b32 s65, v253, 14
	v_readlane_b32 s66, v253, 15
	v_readlane_b32 s67, v253, 16
	v_readlane_b32 s68, v253, 17
	v_readlane_b32 s69, v253, 18
	v_readlane_b32 s70, v253, 19
	v_readlane_b32 s71, v253, 20
	v_writelane_b32 v255, s97, 21
	s_branch .LBB0_306
